# FFN up-projection GEMMs: at a unit boundary the peeled first iteration no longer waits for the previous epilogue's 8 stores at phase 4 (counted vmcnt(16) covers only the prefetched stages; SA(1,1) is
# speedup vs baseline: 1.0004x; 1.0004x over previous
; #define PG8_STAGE(bufoff, gbase, voff) do { _Pragma("unroll") for (int _i = 0; _i < 2; ++_i) \
;         __builtin_amdgcn_global_load_lds((const unsigned*)((const char*)(gbase) + (voff)[_i]), (LAS unsigned*)(lds + (bufoff) + ldsw + _i * 8192), 16, 0, 0); } while (0)
; #define PG8_LDA(dst, b, h) do { _Pragma("unroll") for (int m = 0; m < 4; ++m) _Pragma("unroll") for (int k = 0; k < 2; ++k) dst[m][k] = *(const LAS bf16x8*)(lds + PG8_SA(b, h) + aoff + m * 2048 + k * 1024); } while (0)
; #define PG8_LDB(dst, b, h) do { _Pragma("unroll") for (int n = 0; n < 2; ++n) _Pragma("unroll") for (int k = 0; k < 2; ++k) dst[n][k] = *(const LAS bf16x8*)(lds + PG8_SB(b, h) + boff + n * 2048 + k * 1024); } while (0)
; #define PG8_WAIT_L(n) asm volatile("s_waitcnt lgkmcnt(" #n ")" ::: "memory")
; #define PG8_BAR __builtin_amdgcn_s_barrier()
; #define PG8_SCHED __builtin_amdgcn_sched_barrier(0)
; template <class Epi, class Sched>
; __device__ __forceinline__ void gemm_phase(LAS unsigned char* lds, const Gemm g, const Sched& S, const Epi& E) {
;     ...
;         const bool has_next = S.next(ui + 1, nxt);
;         const char* nA = has_next ? (const char*)g.A + (size_t)nxt.pm * tstep : cA; const char* nB = has_next ? (const char*)g.Bt + (size_t)nxt.pn * tstep : cB;
;         for (int t = 0; t < nt; t += 2) {
;             const bool last = (t == nt - 2);
;             const char* a1 = cA + (size_t)(t + 1) * kstep;
;             const char* a2 = last ? nA : cA + (size_t)(t + 2) * kstep; const char* b2 = last ? nB : cB + (size_t)(t + 2) * kstep;
;             const char* a3 = a2 + kstep; const char* b3 = b2 + kstep;
;             if (last && has_next) S.a_ready(nxt);
;             PG8_LDB(B0, 0, 0); PG8_SCHED; PG8_LDA(At, 0, 0); PG8_STAGE(PG8_SA(1, 1), a1 + hstep, voffA);
;             PG8_WAIT_L(8); PG8_BAR; PG8_WAIT_L(0); PG8_MMA(0, 0, At, B0); PG8_BAR; PG8_SCHED;
;             PG8_LDB(B1, 0, 1); PG8_STAGE(PG8_SB(0, 0), b2, voffB);
;             PG8_BAR; PG8_WAIT_L(0); PG8_MMA(0, 1, At, B1); PG8_BAR;
;             PG8_LDA(At, 0, 1); PG8_STAGE(PG8_SA(0, 0), a2, voffA);
;             PG8_BAR; PG8_WAIT_L(0); PG8_MMA(1, 0, At, B0); PG8_BAR; PG8_SCHED;
;             PG8_STAGE(PG8_SB(0, 1), b2 + hstep, voffB);
.LBB0_242:
	s_ashr_i32 s15, s14, 31
	v_cmp_lt_i64_e32 vcc, s[16:17], v[142:143]
	s_lshl_b64 s[16:17], s[14:15], 20
	s_add_u32 s16, s29, s16
	s_addc_u32 s17, s30, s17
	s_and_b64 s[18:19], vcc, exec
	s_cselect_b32 s15, s17, s23
	s_cselect_b32 s47, s16, s22
	s_ashr_i32 s9, s8, 31
	s_lshl_b64 s[18:19], s[8:9], 20
	s_add_u32 s18, s50, s18
	s_addc_u32 s19, s51, s19
	s_and_b64 s[26:27], vcc, exec
	s_cselect_b32 s9, s19, s25
	s_cselect_b32 s48, s18, s24
	s_add_u32 s22, s22, 0x80080
	s_addc_u32 s23, s23, 0
	s_add_u32 s49, s24, 0x100
	s_addc_u32 s50, s25, 0
	s_mov_b32 s51, -2
	ds_read_b128 v[152:155], v148
	ds_read_b128 v[156:159], v148 offset:1024
	ds_read_b128 v[160:163], v148 offset:2048
	ds_read_b128 v[164:167], v148 offset:3072
	s_add_u32 s24, s22, 0xfff80080
	s_addc_u32 s25, s23, -1
	s_cmp_eq_u32 s51, 28
	s_cselect_b32 s27, s15, s25
	s_cselect_b32 s26, s47, s24
	s_cselect_b32 s25, s9, s50
	s_cselect_b32 s24, s48, s49
	v_lshl_add_u64 v[200:201], s[22:23], 0, v[138:139]
	s_add_i32 m0, s21, 0xc000
	ds_read_b128 v[168:171], v149
	ds_read_b128 v[172:175], v149 offset:1024
	ds_read_b128 v[176:179], v149 offset:2048
	ds_read_b128 v[180:183], v149 offset:3072
	ds_read_b128 v[184:187], v149 offset:4096
	ds_read_b128 v[188:191], v149 offset:5120
	ds_read_b128 v[192:195], v149 offset:6144
	ds_read_b128 v[196:199], v149 offset:7168
	global_load_lds_dwordx4 v[200:201], off
	v_lshl_add_u64 v[200:201], s[22:23], 0, v[140:141]
	s_add_i32 m0, s21, 0xe000
	s_nop 0
	global_load_lds_dwordx4 v[200:201], off
	s_waitcnt lgkmcnt(8)
	s_barrier
	s_waitcnt lgkmcnt(0)
	s_setprio 1
	s_waitcnt lgkmcnt(0)
	v_mfma_f32_16x16x32_bf16 v[126:129], v[152:155], v[168:171], 0
	v_mfma_f32_16x16x32_bf16 v[118:121], v[160:163], v[168:171], 0
	v_mfma_f32_16x16x32_bf16 v[110:113], v[152:155], v[176:179], 0
	v_mfma_f32_16x16x32_bf16 v[102:105], v[160:163], v[176:179], 0
	v_mfma_f32_16x16x32_bf16 v[94:97], v[152:155], v[184:187], 0
	v_mfma_f32_16x16x32_bf16 v[86:89], v[160:163], v[184:187], 0
	v_mfma_f32_16x16x32_bf16 v[78:81], v[152:155], v[192:195], 0
	v_mfma_f32_16x16x32_bf16 v[70:73], v[160:163], v[192:195], 0
	v_mfma_f32_16x16x32_bf16 v[126:129], v[156:159], v[172:175], v[126:129]
	v_mfma_f32_16x16x32_bf16 v[118:121], v[164:167], v[172:175], v[118:121]
	v_mfma_f32_16x16x32_bf16 v[110:113], v[156:159], v[180:183], v[110:113]
	v_mfma_f32_16x16x32_bf16 v[102:105], v[164:167], v[180:183], v[102:105]
	v_mfma_f32_16x16x32_bf16 v[94:97], v[156:159], v[188:191], v[94:97]
	v_mfma_f32_16x16x32_bf16 v[86:89], v[164:167], v[188:191], v[86:89]
	v_mfma_f32_16x16x32_bf16 v[78:81], v[156:159], v[196:199], v[78:81]
	v_mfma_f32_16x16x32_bf16 v[70:73], v[164:167], v[196:199], v[70:73]
	s_setprio 0
	s_barrier
	s_add_i32 s52, s43, s31
	v_lshl_add_u64 v[204:205], s[24:25], 0, v[132:133]
	s_mov_b32 m0, s52
	ds_read_b128 v[200:203], v150
	ds_read_b128 v[208:211], v150 offset:1024
	ds_read_b128 v[212:215], v150 offset:2048
	ds_read_b128 v[216:219], v150 offset:3072
	global_load_lds_dwordx4 v[204:205], off
	v_lshl_add_u64 v[220:221], s[24:25], 0, v[136:137]
	s_add_i32 m0, s52, 0x2000
	s_nop 0
	global_load_lds_dwordx4 v[220:221], off
	s_barrier
	s_waitcnt lgkmcnt(0)
	s_setprio 1
	s_waitcnt lgkmcnt(0)
	v_mfma_f32_16x16x32_bf16 v[122:125], v[200:203], v[168:171], 0
	v_mfma_f32_16x16x32_bf16 v[114:117], v[212:215], v[168:171], 0
	v_mfma_f32_16x16x32_bf16 v[106:109], v[200:203], v[176:179], 0
	v_mfma_f32_16x16x32_bf16 v[98:101], v[212:215], v[176:179], 0
	v_mfma_f32_16x16x32_bf16 v[90:93], v[200:203], v[184:187], 0
	v_mfma_f32_16x16x32_bf16 v[82:85], v[212:215], v[184:187], 0
	v_mfma_f32_16x16x32_bf16 v[74:77], v[200:203], v[192:195], 0
	v_mfma_f32_16x16x32_bf16 v[66:69], v[212:215], v[192:195], 0
	v_mfma_f32_16x16x32_bf16 v[122:125], v[208:211], v[172:175], v[122:125]
	v_mfma_f32_16x16x32_bf16 v[114:117], v[216:219], v[172:175], v[114:117]
	v_mfma_f32_16x16x32_bf16 v[106:109], v[208:211], v[180:183], v[106:109]
	v_mfma_f32_16x16x32_bf16 v[98:101], v[216:219], v[180:183], v[98:101]
	v_mfma_f32_16x16x32_bf16 v[90:93], v[208:211], v[188:191], v[90:93]
	v_mfma_f32_16x16x32_bf16 v[82:85], v[216:219], v[188:191], v[82:85]
	v_mfma_f32_16x16x32_bf16 v[74:77], v[208:211], v[196:199], v[74:77]
	v_mfma_f32_16x16x32_bf16 v[66:69], v[216:219], v[196:199], v[66:69]
	s_setprio 0
	s_mov_b32 m0, s21
	v_lshl_add_u64 v[222:223], s[26:27], 0, v[130:131]
	s_barrier
	ds_read_b128 v[168:171], v149 offset:16384
	ds_read_b128 v[172:175], v149 offset:17408
	ds_read_b128 v[176:179], v149 offset:18432
	ds_read_b128 v[180:183], v149 offset:19456
	ds_read_b128 v[184:187], v149 offset:20480
	ds_read_b128 v[188:191], v149 offset:21504
	ds_read_b128 v[192:195], v149 offset:22528
	ds_read_b128 v[196:199], v149 offset:23552
	global_load_lds_dwordx4 v[222:223], off
	v_lshl_add_u64 v[224:225], s[26:27], 0, v[134:135]
	s_mov_b32 m0, s35
	s_nop 0
	global_load_lds_dwordx4 v[224:225], off
	s_barrier
	s_waitcnt lgkmcnt(0)
	s_setprio 1
	s_waitcnt lgkmcnt(0)
	v_mfma_f32_16x16x32_bf16 v[62:65], v[152:155], v[168:171], 0
	v_mfma_f32_16x16x32_bf16 v[54:57], v[160:163], v[168:171], 0
	v_mfma_f32_16x16x32_bf16 v[46:49], v[152:155], v[176:179], 0
	v_mfma_f32_16x16x32_bf16 v[38:41], v[160:163], v[176:179], 0
	v_mfma_f32_16x16x32_bf16 v[30:33], v[152:155], v[184:187], 0
	v_mfma_f32_16x16x32_bf16 v[22:25], v[160:163], v[184:187], 0
	v_mfma_f32_16x16x32_bf16 v[14:17], v[152:155], v[192:195], 0
	v_mfma_f32_16x16x32_bf16 v[6:9], v[160:163], v[192:195], 0
	v_mfma_f32_16x16x32_bf16 v[62:65], v[156:159], v[172:175], v[62:65]
	v_mfma_f32_16x16x32_bf16 v[54:57], v[164:167], v[172:175], v[54:57]
	v_mfma_f32_16x16x32_bf16 v[46:49], v[156:159], v[180:183], v[46:49]
	v_mfma_f32_16x16x32_bf16 v[38:41], v[164:167], v[180:183], v[38:41]
	v_mfma_f32_16x16x32_bf16 v[30:33], v[156:159], v[188:191], v[30:33]
	v_mfma_f32_16x16x32_bf16 v[22:25], v[164:167], v[188:191], v[22:25]
	v_mfma_f32_16x16x32_bf16 v[14:17], v[156:159], v[196:199], v[14:17]
	v_mfma_f32_16x16x32_bf16 v[6:9], v[164:167], v[196:199], v[6:9]
	s_setprio 0
	s_barrier
	s_add_u32 s52, s24, 0x80000
	s_addc_u32 s53, s25, 0
	s_add_i32 s54, s44, s31
	v_lshl_add_u64 v[152:153], s[52:53], 0, v[132:133]
	s_mov_b32 m0, s54
	s_nop 0
	global_load_lds_dwordx4 v[152:153], off
	v_lshl_add_u64 v[152:153], s[52:53], 0, v[136:137]
	s_add_i32 m0, s54, 0x2000
	s_nop 0
	global_load_lds_dwordx4 v[152:153], off
	s_cmp_eq_u32 s38, 1
	s_cbranch_scc1 .Lpw_p1_strict
	s_waitcnt vmcnt(16)
	s_branch .Lpw_p1_go
; #define PG8_STAGE(bufoff, gbase, voff) do { _Pragma("unroll") for (int _i = 0; _i < 2; ++_i) \
;         __builtin_amdgcn_global_load_lds((const unsigned*)((const char*)(gbase) + (voff)[_i]), (LAS unsigned*)(lds + (bufoff) + ldsw + _i * 8192), 16, 0, 0); } while (0)
; #define PG8_LDA(dst, b, h) do { _Pragma("unroll") for (int m = 0; m < 4; ++m) _Pragma("unroll") for (int k = 0; k < 2; ++k) dst[m][k] = *(const LAS bf16x8*)(lds + PG8_SA(b, h) + aoff + m * 2048 + k * 1024); } while (0)
; #define PG8_LDB(dst, b, h) do { _Pragma("unroll") for (int n = 0; n < 2; ++n) _Pragma("unroll") for (int k = 0; k < 2; ++k) dst[n][k] = *(const LAS bf16x8*)(lds + PG8_SB(b, h) + boff + n * 2048 + k * 1024); } while (0)
; #define PG8_MMA(ai, bj, At, Bt) do { __builtin_amdgcn_s_setprio(1); _Pragma("unroll") for (int m = 0; m < 4; ++m) _Pragma("unroll") for (int n = 0; n < 2; ++n) _Pragma("unroll") for (int k = 0; k < 2; ++k) \
;         acc[ai][bj][m][n] = __builtin_amdgcn_mfma_f32_16x16x32_bf16(Bt[n][k], At[m][k], acc[ai][bj][m][n], 0, 0, 0); __builtin_amdgcn_s_setprio(0); } while (0)
; #define PG8_WAIT_V(n) asm volatile("s_waitcnt vmcnt(" #n ")" ::: "memory")
; #define PG8_WAIT_L(n) asm volatile("s_waitcnt lgkmcnt(" #n ")" ::: "memory")
; #define PG8_BAR __builtin_amdgcn_s_barrier()
; #define PG8_SCHED __builtin_amdgcn_sched_barrier(0)
; template <class Epi, class Sched>
; __device__ __forceinline__ void gemm_phase(LAS unsigned char* lds, const Gemm g, const Sched& S, const Epi& E) {
;     ...
;             PG8_WAIT_V(6); PG8_BAR; PG8_MMA(1, 1, At, B1); PG8_BAR;
;             PG8_LDB(B0, 1, 0); PG8_SCHED; PG8_LDA(At, 1, 0); PG8_STAGE(PG8_SA(0, 1), a2 + hstep, voffA);
;             PG8_WAIT_L(8); PG8_BAR; PG8_WAIT_L(0); PG8_MMA(0, 0, At, B0); PG8_BAR; PG8_SCHED;
;             PG8_LDB(B1, 1, 1); PG8_STAGE(PG8_SB(1, 0), b3, voffB);
.Lpw_p1_strict:
	s_waitcnt vmcnt(6)
.Lpw_p1_go:
	s_barrier
	s_setprio 1
	v_mfma_f32_16x16x32_bf16 v[58:61], v[200:203], v[168:171], 0
	v_mfma_f32_16x16x32_bf16 v[50:53], v[212:215], v[168:171], 0
	v_mfma_f32_16x16x32_bf16 v[42:45], v[200:203], v[176:179], 0
	v_mfma_f32_16x16x32_bf16 v[34:37], v[212:215], v[176:179], 0
	v_mfma_f32_16x16x32_bf16 v[26:29], v[200:203], v[184:187], 0
	v_mfma_f32_16x16x32_bf16 v[18:21], v[212:215], v[184:187], 0
	v_mfma_f32_16x16x32_bf16 v[10:13], v[200:203], v[192:195], 0
	v_mfma_f32_16x16x32_bf16 v[2:5], v[212:215], v[192:195], 0
	v_mfma_f32_16x16x32_bf16 v[58:61], v[208:211], v[172:175], v[58:61]
	v_mfma_f32_16x16x32_bf16 v[50:53], v[216:219], v[172:175], v[50:53]
	v_mfma_f32_16x16x32_bf16 v[42:45], v[208:211], v[180:183], v[42:45]
	v_mfma_f32_16x16x32_bf16 v[34:37], v[216:219], v[180:183], v[34:37]
	v_mfma_f32_16x16x32_bf16 v[26:29], v[208:211], v[188:191], v[26:29]
	v_mfma_f32_16x16x32_bf16 v[18:21], v[216:219], v[188:191], v[18:21]
	v_mfma_f32_16x16x32_bf16 v[10:13], v[208:211], v[196:199], v[10:13]
	v_mfma_f32_16x16x32_bf16 v[2:5], v[216:219], v[196:199], v[2:5]
	s_setprio 0
	s_add_i32 s52, 0, 0x18000
	v_add_u32_e32 v151, s52, v146
	s_barrier
	ds_read_b128 v[152:155], v151
	ds_read_b128 v[156:159], v151 offset:1024
	ds_read_b128 v[160:163], v151 offset:2048
	ds_read_b128 v[164:167], v151 offset:3072
	s_add_u32 s26, s26, 0x80000
	s_addc_u32 s27, s27, 0
	s_mov_b32 m0, s36
	v_lshl_add_u64 v[200:201], s[26:27], 0, v[130:131]
	ds_read_b128 v[168:171], v149 offset:32768
	ds_read_b128 v[172:175], v149 offset:33792
	ds_read_b128 v[176:179], v149 offset:34816
	ds_read_b128 v[180:183], v149 offset:35840
	ds_read_b128 v[184:187], v149 offset:36864
	ds_read_b128 v[188:191], v149 offset:37888
	ds_read_b128 v[192:195], v149 offset:38912
	ds_read_b128 v[196:199], v149 offset:39936
	global_load_lds_dwordx4 v[200:201], off
	v_lshl_add_u64 v[200:201], s[26:27], 0, v[134:135]
	s_mov_b32 m0, s37
	s_nop 0
	global_load_lds_dwordx4 v[200:201], off
	s_waitcnt lgkmcnt(8)
	s_barrier
	s_waitcnt lgkmcnt(0)
	s_setprio 1
	s_waitcnt lgkmcnt(0)
	v_mfma_f32_16x16x32_bf16 v[126:129], v[152:155], v[168:171], v[126:129]
	v_mfma_f32_16x16x32_bf16 v[118:121], v[160:163], v[168:171], v[118:121]
	v_mfma_f32_16x16x32_bf16 v[110:113], v[152:155], v[176:179], v[110:113]
	v_mfma_f32_16x16x32_bf16 v[102:105], v[160:163], v[176:179], v[102:105]
	v_mfma_f32_16x16x32_bf16 v[94:97], v[152:155], v[184:187], v[94:97]
	v_mfma_f32_16x16x32_bf16 v[86:89], v[160:163], v[184:187], v[86:89]
	v_mfma_f32_16x16x32_bf16 v[78:81], v[152:155], v[192:195], v[78:81]
	v_mfma_f32_16x16x32_bf16 v[70:73], v[160:163], v[192:195], v[70:73]
	v_mfma_f32_16x16x32_bf16 v[126:129], v[156:159], v[172:175], v[126:129]
	v_mfma_f32_16x16x32_bf16 v[118:121], v[164:167], v[172:175], v[118:121]
	v_mfma_f32_16x16x32_bf16 v[110:113], v[156:159], v[180:183], v[110:113]
	v_mfma_f32_16x16x32_bf16 v[102:105], v[164:167], v[180:183], v[102:105]
	v_mfma_f32_16x16x32_bf16 v[94:97], v[156:159], v[188:191], v[94:97]
	v_mfma_f32_16x16x32_bf16 v[86:89], v[164:167], v[188:191], v[86:89]
	v_mfma_f32_16x16x32_bf16 v[78:81], v[156:159], v[196:199], v[78:81]
	v_mfma_f32_16x16x32_bf16 v[70:73], v[164:167], v[196:199], v[70:73]
	s_setprio 0
	s_barrier
	s_add_i32 s26, 0, 0x1c000
	s_add_i32 s27, s52, s31
	v_add_u32_e32 v151, s26, v146
	v_lshl_add_u64 v[204:205], v[204:205], 0, s[6:7]
	s_mov_b32 m0, s27
	ds_read_b128 v[200:203], v151
	ds_read_b128 v[208:211], v151 offset:1024
	ds_read_b128 v[212:215], v151 offset:2048
	ds_read_b128 v[216:219], v151 offset:3072
	global_load_lds_dwordx4 v[204:205], off
	v_lshl_add_u64 v[204:205], v[220:221], 0, s[6:7]
	s_add_i32 m0, s27, 0x2000
	s_nop 0
	global_load_lds_dwordx4 v[204:205], off
	s_barrier
; #define PG8_STAGE(bufoff, gbase, voff) do { _Pragma("unroll") for (int _i = 0; _i < 2; ++_i) \
;         __builtin_amdgcn_global_load_lds((const unsigned*)((const char*)(gbase) + (voff)[_i]), (LAS unsigned*)(lds + (bufoff) + ldsw + _i * 8192), 16, 0, 0); } while (0)
; #define PG8_LDA(dst, b, h) do { _Pragma("unroll") for (int m = 0; m < 4; ++m) _Pragma("unroll") for (int k = 0; k < 2; ++k) dst[m][k] = *(const LAS bf16x8*)(lds + PG8_SA(b, h) + aoff + m * 2048 + k * 1024); } while (0)
; #define PG8_MMA(ai, bj, At, Bt) do { __builtin_amdgcn_s_setprio(1); _Pragma("unroll") for (int m = 0; m < 4; ++m) _Pragma("unroll") for (int n = 0; n < 2; ++n) _Pragma("unroll") for (int k = 0; k < 2; ++k) \
;         acc[ai][bj][m][n] = __builtin_amdgcn_mfma_f32_16x16x32_bf16(Bt[n][k], At[m][k], acc[ai][bj][m][n], 0, 0, 0); __builtin_amdgcn_s_setprio(0); } while (0)
; #define PG8_WAIT_V(n) asm volatile("s_waitcnt vmcnt(" #n ")" ::: "memory")
; #define PG8_WAIT_L(n) asm volatile("s_waitcnt lgkmcnt(" #n ")" ::: "memory")
; #define PG8_BAR __builtin_amdgcn_s_barrier()
; #define PG8_SCHED __builtin_amdgcn_sched_barrier(0)
; template <class Epi, class Sched>
; __device__ __forceinline__ void gemm_phase(LAS unsigned char* lds, const Gemm g, const Sched& S, const Epi& E) {
;     ...
;             PG8_BAR; PG8_WAIT_L(0); PG8_MMA(0, 1, At, B1); PG8_BAR;
;             PG8_LDA(At, 1, 1); PG8_STAGE(PG8_SA(1, 0), a3, voffA);
;             PG8_BAR; PG8_WAIT_L(0); PG8_MMA(1, 0, At, B0); PG8_BAR; PG8_SCHED;
;             PG8_STAGE(PG8_SB(1, 1), b3 + hstep, voffB);
;             PG8_WAIT_V(6); PG8_BAR; PG8_MMA(1, 1, At, B1); PG8_BAR;
	s_waitcnt lgkmcnt(0)
	s_setprio 1
	s_waitcnt lgkmcnt(0)
	v_mfma_f32_16x16x32_bf16 v[122:125], v[200:203], v[168:171], v[122:125]
	v_mfma_f32_16x16x32_bf16 v[114:117], v[212:215], v[168:171], v[114:117]
	v_mfma_f32_16x16x32_bf16 v[106:109], v[200:203], v[176:179], v[106:109]
	v_mfma_f32_16x16x32_bf16 v[98:101], v[212:215], v[176:179], v[98:101]
	v_mfma_f32_16x16x32_bf16 v[90:93], v[200:203], v[184:187], v[90:93]
	v_mfma_f32_16x16x32_bf16 v[82:85], v[212:215], v[184:187], v[82:85]
	v_mfma_f32_16x16x32_bf16 v[74:77], v[200:203], v[192:195], v[74:77]
	v_mfma_f32_16x16x32_bf16 v[66:69], v[212:215], v[192:195], v[66:69]
	v_mfma_f32_16x16x32_bf16 v[122:125], v[208:211], v[172:175], v[122:125]
	v_mfma_f32_16x16x32_bf16 v[114:117], v[216:219], v[172:175], v[114:117]
	v_mfma_f32_16x16x32_bf16 v[106:109], v[208:211], v[180:183], v[106:109]
	v_mfma_f32_16x16x32_bf16 v[98:101], v[216:219], v[180:183], v[98:101]
	v_mfma_f32_16x16x32_bf16 v[90:93], v[208:211], v[188:191], v[90:93]
	v_mfma_f32_16x16x32_bf16 v[82:85], v[216:219], v[188:191], v[82:85]
	v_mfma_f32_16x16x32_bf16 v[74:77], v[208:211], v[196:199], v[74:77]
	v_mfma_f32_16x16x32_bf16 v[66:69], v[216:219], v[196:199], v[66:69]
	s_setprio 0
	s_mov_b32 m0, s40
	v_lshl_add_u64 v[204:205], v[222:223], 0, s[6:7]
	s_waitcnt vmcnt(10)
	s_barrier
	ds_read_b128 v[168:171], v149 offset:49152
	ds_read_b128 v[172:175], v149 offset:50176
	ds_read_b128 v[176:179], v149 offset:51200
	ds_read_b128 v[180:183], v149 offset:52224
	ds_read_b128 v[184:187], v149 offset:53248
	ds_read_b128 v[188:191], v149 offset:54272
	ds_read_b128 v[192:195], v149 offset:55296
	ds_read_b128 v[196:199], v149 offset:56320
	global_load_lds_dwordx4 v[204:205], off
	v_lshl_add_u64 v[204:205], v[224:225], 0, s[6:7]
	s_mov_b32 m0, s41
	s_nop 0
	global_load_lds_dwordx4 v[204:205], off
	s_barrier
	s_waitcnt lgkmcnt(0)
	s_setprio 1
	s_waitcnt lgkmcnt(0)
	v_mfma_f32_16x16x32_bf16 v[62:65], v[152:155], v[168:171], v[62:65]
	v_mfma_f32_16x16x32_bf16 v[54:57], v[160:163], v[168:171], v[54:57]
	v_mfma_f32_16x16x32_bf16 v[46:49], v[152:155], v[176:179], v[46:49]
	v_mfma_f32_16x16x32_bf16 v[38:41], v[160:163], v[176:179], v[38:41]
	v_mfma_f32_16x16x32_bf16 v[30:33], v[152:155], v[184:187], v[30:33]
	v_mfma_f32_16x16x32_bf16 v[22:25], v[160:163], v[184:187], v[22:25]
	v_mfma_f32_16x16x32_bf16 v[14:17], v[152:155], v[192:195], v[14:17]
	v_mfma_f32_16x16x32_bf16 v[6:9], v[160:163], v[192:195], v[6:9]
	v_mfma_f32_16x16x32_bf16 v[62:65], v[156:159], v[172:175], v[62:65]
	v_mfma_f32_16x16x32_bf16 v[54:57], v[164:167], v[172:175], v[54:57]
	v_mfma_f32_16x16x32_bf16 v[46:49], v[156:159], v[180:183], v[46:49]
	v_mfma_f32_16x16x32_bf16 v[38:41], v[164:167], v[180:183], v[38:41]
	v_mfma_f32_16x16x32_bf16 v[30:33], v[156:159], v[188:191], v[30:33]
	v_mfma_f32_16x16x32_bf16 v[22:25], v[164:167], v[188:191], v[22:25]
	v_mfma_f32_16x16x32_bf16 v[14:17], v[156:159], v[196:199], v[14:17]
	v_mfma_f32_16x16x32_bf16 v[6:9], v[164:167], v[196:199], v[6:9]
	s_setprio 0
	s_barrier
	s_add_u32 s24, s24, 0x80080
	s_addc_u32 s25, s25, 0
	s_add_i32 s26, s26, s31
	v_lshl_add_u64 v[152:153], s[24:25], 0, v[132:133]
	s_mov_b32 m0, s26
	s_nop 0
	global_load_lds_dwordx4 v[152:153], off
	v_lshl_add_u64 v[152:153], s[24:25], 0, v[136:137]
	s_add_i32 m0, s26, 0x2000
	s_nop 0
	global_load_lds_dwordx4 v[152:153], off
	s_waitcnt vmcnt(6)
	s_barrier
	s_setprio 1
	v_mfma_f32_16x16x32_bf16 v[58:61], v[200:203], v[168:171], v[58:61]
	v_mfma_f32_16x16x32_bf16 v[50:53], v[212:215], v[168:171], v[50:53]
	v_mfma_f32_16x16x32_bf16 v[42:45], v[200:203], v[176:179], v[42:45]
	v_mfma_f32_16x16x32_bf16 v[34:37], v[212:215], v[176:179], v[34:37]
	v_mfma_f32_16x16x32_bf16 v[26:29], v[200:203], v[184:187], v[26:29]
	v_mfma_f32_16x16x32_bf16 v[18:21], v[212:215], v[184:187], v[18:21]
	v_mfma_f32_16x16x32_bf16 v[10:13], v[200:203], v[192:195], v[10:13]
	v_mfma_f32_16x16x32_bf16 v[2:5], v[212:215], v[192:195], v[2:5]
	v_mfma_f32_16x16x32_bf16 v[58:61], v[208:211], v[172:175], v[58:61]
	v_mfma_f32_16x16x32_bf16 v[50:53], v[216:219], v[172:175], v[50:53]
	v_mfma_f32_16x16x32_bf16 v[42:45], v[208:211], v[180:183], v[42:45]
	v_mfma_f32_16x16x32_bf16 v[34:37], v[216:219], v[180:183], v[34:37]
	v_mfma_f32_16x16x32_bf16 v[26:29], v[208:211], v[188:191], v[26:29]
	v_mfma_f32_16x16x32_bf16 v[18:21], v[216:219], v[188:191], v[18:21]
	v_mfma_f32_16x16x32_bf16 v[10:13], v[208:211], v[196:199], v[10:13]
	v_mfma_f32_16x16x32_bf16 v[2:5], v[216:219], v[196:199], v[2:5]
	s_setprio 0
	s_add_i32 s51, s51, 2
	s_add_u32 s22, s22, 0x100
	s_addc_u32 s23, s23, 0
	s_add_u32 s49, s49, 0x100
	s_addc_u32 s50, s50, 0
	s_cmp_gt_u32 s51, 29
	s_barrier

; #define PG8_STAGE(bufoff, gbase, voff) do { _Pragma("unroll") for (int _i = 0; _i < 2; ++_i) \
;         __builtin_amdgcn_global_load_lds((const unsigned*)((const char*)(gbase) + (voff)[_i]), (LAS unsigned*)(lds + (bufoff) + ldsw + _i * 8192), 16, 0, 0); } while (0)
; #define PG8_LDA(dst, b, h) do { _Pragma("unroll") for (int m = 0; m < 4; ++m) _Pragma("unroll") for (int k = 0; k < 2; ++k) dst[m][k] = *(const LAS bf16x8*)(lds + PG8_SA(b, h) + aoff + m * 2048 + k * 1024); } while (0)
; #define PG8_LDB(dst, b, h) do { _Pragma("unroll") for (int n = 0; n < 2; ++n) _Pragma("unroll") for (int k = 0; k < 2; ++k) dst[n][k] = *(const LAS bf16x8*)(lds + PG8_SB(b, h) + boff + n * 2048 + k * 1024); } while (0)
; #define PG8_WAIT_L(n) asm volatile("s_waitcnt lgkmcnt(" #n ")" ::: "memory")
; #define PG8_BAR __builtin_amdgcn_s_barrier()
; #define PG8_SCHED __builtin_amdgcn_sched_barrier(0)
; template <class Epi, class Sched>
; __device__ __forceinline__ void gemm_phase(LAS unsigned char* lds, const Gemm g, const Sched& S, const Epi& E) {
;     ...
;         const bool has_next = S.next(ui + 1, nxt);
;         const char* nA = has_next ? (const char*)g.A + (size_t)nxt.pm * tstep : cA; const char* nB = has_next ? (const char*)g.Bt + (size_t)nxt.pn * tstep : cB;
;         for (int t = 0; t < nt; t += 2) {
;             const bool last = (t == nt - 2);
;             const char* a1 = cA + (size_t)(t + 1) * kstep;
;             const char* a2 = last ? nA : cA + (size_t)(t + 2) * kstep; const char* b2 = last ? nB : cB + (size_t)(t + 2) * kstep;
;             const char* a3 = a2 + kstep; const char* b3 = b2 + kstep;
;             if (last && has_next) S.a_ready(nxt);
;             PG8_LDB(B0, 0, 0); PG8_SCHED; PG8_LDA(At, 0, 0); PG8_STAGE(PG8_SA(1, 1), a1 + hstep, voffA);
;             PG8_WAIT_L(8); PG8_BAR; PG8_WAIT_L(0); PG8_MMA(0, 0, At, B0); PG8_BAR; PG8_SCHED;
;             PG8_LDB(B1, 0, 1); PG8_STAGE(PG8_SB(0, 0), b2, voffB);
;             PG8_BAR; PG8_WAIT_L(0); PG8_MMA(0, 1, At, B1); PG8_BAR;
;             PG8_LDA(At, 0, 1); PG8_STAGE(PG8_SA(0, 0), a2, voffA);
;             PG8_BAR; PG8_WAIT_L(0); PG8_MMA(1, 0, At, B0); PG8_BAR; PG8_SCHED;
;             PG8_STAGE(PG8_SB(0, 1), b2 + hstep, voffB);
.LBB0_1090:
	s_ashr_i32 s11, s10, 31
	v_cmp_lt_i64_e32 vcc, s[12:13], v[142:143]
	s_lshl_b64 s[12:13], s[10:11], 20
	s_add_u32 s12, s28, s12
	s_addc_u32 s13, s29, s13
	s_and_b64 s[14:15], vcc, exec
	s_cselect_b32 s11, s13, s19
	s_cselect_b32 s45, s12, s18
	s_ashr_i32 s9, s8, 31
	s_lshl_b64 s[14:15], s[8:9], 20
	s_add_u32 s14, s30, s14
	s_addc_u32 s15, s31, s15
	s_and_b64 s[22:23], vcc, exec
	s_cselect_b32 s9, s15, s21
	s_cselect_b32 s46, s14, s20
	s_add_u32 s18, s18, 0x80080
	s_addc_u32 s19, s19, 0
	s_add_u32 s47, s20, 0x100
	s_addc_u32 s48, s21, 0
	s_mov_b32 s49, -2
	ds_read_b128 v[152:155], v149
	ds_read_b128 v[156:159], v149 offset:1024
	ds_read_b128 v[160:163], v149 offset:2048
	ds_read_b128 v[164:167], v149 offset:3072
	s_add_u32 s20, s18, 0xfff80080
	s_addc_u32 s21, s19, -1
	s_cmp_eq_u32 s49, 28
	s_cselect_b32 s23, s11, s21
	s_cselect_b32 s22, s45, s20
	s_cselect_b32 s21, s9, s48
	s_cselect_b32 s20, s46, s47
	v_lshl_add_u64 v[200:201], s[18:19], 0, v[138:139]
	s_add_i32 m0, s17, 0xc000
	ds_read_b128 v[168:171], v150
	ds_read_b128 v[172:175], v150 offset:1024
	ds_read_b128 v[176:179], v150 offset:2048
	ds_read_b128 v[180:183], v150 offset:3072
	ds_read_b128 v[184:187], v150 offset:4096
	ds_read_b128 v[188:191], v150 offset:5120
	ds_read_b128 v[192:195], v150 offset:6144
	ds_read_b128 v[196:199], v150 offset:7168
	global_load_lds_dwordx4 v[200:201], off
	v_lshl_add_u64 v[200:201], s[18:19], 0, v[140:141]
	s_add_i32 m0, s17, 0xe000
	s_nop 0
	global_load_lds_dwordx4 v[200:201], off
	s_waitcnt lgkmcnt(8)
	s_barrier
	s_waitcnt lgkmcnt(0)
	s_setprio 1
	s_waitcnt lgkmcnt(0)
	v_mfma_f32_16x16x32_bf16 v[126:129], v[152:155], v[168:171], 0
	v_mfma_f32_16x16x32_bf16 v[122:125], v[160:163], v[168:171], 0
	v_mfma_f32_16x16x32_bf16 v[110:113], v[152:155], v[176:179], 0
	v_mfma_f32_16x16x32_bf16 v[106:109], v[160:163], v[176:179], 0
	v_mfma_f32_16x16x32_bf16 v[94:97], v[152:155], v[184:187], 0
	v_mfma_f32_16x16x32_bf16 v[90:93], v[160:163], v[184:187], 0
	v_mfma_f32_16x16x32_bf16 v[78:81], v[152:155], v[192:195], 0
	v_mfma_f32_16x16x32_bf16 v[74:77], v[160:163], v[192:195], 0
	v_mfma_f32_16x16x32_bf16 v[126:129], v[156:159], v[172:175], v[126:129]
	v_mfma_f32_16x16x32_bf16 v[122:125], v[164:167], v[172:175], v[122:125]
	v_mfma_f32_16x16x32_bf16 v[110:113], v[156:159], v[180:183], v[110:113]
	v_mfma_f32_16x16x32_bf16 v[106:109], v[164:167], v[180:183], v[106:109]
	v_mfma_f32_16x16x32_bf16 v[94:97], v[156:159], v[188:191], v[94:97]
	v_mfma_f32_16x16x32_bf16 v[90:93], v[164:167], v[188:191], v[90:93]
	v_mfma_f32_16x16x32_bf16 v[78:81], v[156:159], v[196:199], v[78:81]
	v_mfma_f32_16x16x32_bf16 v[74:77], v[164:167], v[196:199], v[74:77]
	s_setprio 0
	s_barrier
	s_add_i32 s50, s39, s27
	v_lshl_add_u64 v[204:205], s[20:21], 0, v[132:133]
	s_mov_b32 m0, s50
	ds_read_b128 v[200:203], v151
	ds_read_b128 v[208:211], v151 offset:1024
	ds_read_b128 v[212:215], v151 offset:2048
	ds_read_b128 v[216:219], v151 offset:3072
	global_load_lds_dwordx4 v[204:205], off
	v_lshl_add_u64 v[220:221], s[20:21], 0, v[136:137]
	s_add_i32 m0, s50, 0x2000
	s_nop 0
	global_load_lds_dwordx4 v[220:221], off
	s_barrier
	s_waitcnt lgkmcnt(0)
	s_setprio 1
	s_waitcnt lgkmcnt(0)
	v_mfma_f32_16x16x32_bf16 v[118:121], v[200:203], v[168:171], 0
	v_mfma_f32_16x16x32_bf16 v[114:117], v[212:215], v[168:171], 0
	v_mfma_f32_16x16x32_bf16 v[102:105], v[200:203], v[176:179], 0
	v_mfma_f32_16x16x32_bf16 v[98:101], v[212:215], v[176:179], 0
	v_mfma_f32_16x16x32_bf16 v[86:89], v[200:203], v[184:187], 0
	v_mfma_f32_16x16x32_bf16 v[82:85], v[212:215], v[184:187], 0
	v_mfma_f32_16x16x32_bf16 v[70:73], v[200:203], v[192:195], 0
	v_mfma_f32_16x16x32_bf16 v[66:69], v[212:215], v[192:195], 0
	v_mfma_f32_16x16x32_bf16 v[118:121], v[208:211], v[172:175], v[118:121]
	v_mfma_f32_16x16x32_bf16 v[114:117], v[216:219], v[172:175], v[114:117]
	v_mfma_f32_16x16x32_bf16 v[102:105], v[208:211], v[180:183], v[102:105]
	v_mfma_f32_16x16x32_bf16 v[98:101], v[216:219], v[180:183], v[98:101]
	v_mfma_f32_16x16x32_bf16 v[86:89], v[208:211], v[188:191], v[86:89]
	v_mfma_f32_16x16x32_bf16 v[82:85], v[216:219], v[188:191], v[82:85]
	v_mfma_f32_16x16x32_bf16 v[70:73], v[208:211], v[196:199], v[70:73]
	v_mfma_f32_16x16x32_bf16 v[66:69], v[216:219], v[196:199], v[66:69]
	s_setprio 0
	s_mov_b32 m0, s17
	v_lshl_add_u64 v[222:223], s[22:23], 0, v[130:131]
	s_barrier
	ds_read_b128 v[168:171], v150 offset:16384
	ds_read_b128 v[172:175], v150 offset:17408
	ds_read_b128 v[176:179], v150 offset:18432
	ds_read_b128 v[180:183], v150 offset:19456
	ds_read_b128 v[184:187], v150 offset:20480
	ds_read_b128 v[188:191], v150 offset:21504
	ds_read_b128 v[192:195], v150 offset:22528
	ds_read_b128 v[196:199], v150 offset:23552
	global_load_lds_dwordx4 v[222:223], off
	v_lshl_add_u64 v[224:225], s[22:23], 0, v[134:135]
	s_mov_b32 m0, s34
	s_nop 0
	global_load_lds_dwordx4 v[224:225], off
	s_barrier
	s_waitcnt lgkmcnt(0)
	s_setprio 1
	s_waitcnt lgkmcnt(0)
	v_mfma_f32_16x16x32_bf16 v[62:65], v[152:155], v[168:171], 0
	v_mfma_f32_16x16x32_bf16 v[58:61], v[160:163], v[168:171], 0
	v_mfma_f32_16x16x32_bf16 v[46:49], v[152:155], v[176:179], 0
	v_mfma_f32_16x16x32_bf16 v[42:45], v[160:163], v[176:179], 0
	v_mfma_f32_16x16x32_bf16 v[30:33], v[152:155], v[184:187], 0
	v_mfma_f32_16x16x32_bf16 v[26:29], v[160:163], v[184:187], 0
	v_mfma_f32_16x16x32_bf16 v[14:17], v[152:155], v[192:195], 0
	v_mfma_f32_16x16x32_bf16 v[10:13], v[160:163], v[192:195], 0
	v_mfma_f32_16x16x32_bf16 v[62:65], v[156:159], v[172:175], v[62:65]
	v_mfma_f32_16x16x32_bf16 v[58:61], v[164:167], v[172:175], v[58:61]
	v_mfma_f32_16x16x32_bf16 v[46:49], v[156:159], v[180:183], v[46:49]
	v_mfma_f32_16x16x32_bf16 v[42:45], v[164:167], v[180:183], v[42:45]
	v_mfma_f32_16x16x32_bf16 v[30:33], v[156:159], v[188:191], v[30:33]
	v_mfma_f32_16x16x32_bf16 v[26:29], v[164:167], v[188:191], v[26:29]
	v_mfma_f32_16x16x32_bf16 v[14:17], v[156:159], v[196:199], v[14:17]
	v_mfma_f32_16x16x32_bf16 v[10:13], v[164:167], v[196:199], v[10:13]
	s_setprio 0
	s_barrier
	s_add_u32 s50, s20, 0x80000
	s_addc_u32 s51, s21, 0
	s_add_i32 s52, s40, s27
	v_lshl_add_u64 v[152:153], s[50:51], 0, v[132:133]
	s_mov_b32 m0, s52
	s_nop 0
	global_load_lds_dwordx4 v[152:153], off
	v_lshl_add_u64 v[152:153], s[50:51], 0, v[136:137]
	s_add_i32 m0, s52, 0x2000
	s_nop 0
	global_load_lds_dwordx4 v[152:153], off
	s_cmp_eq_u32 s43, 0
	s_cbranch_scc1 .Lpw_p10_strict
	s_waitcnt vmcnt(16)
	s_branch .Lpw_p10_go

; #define PG8_STAGE(bufoff, gbase, voff) do { _Pragma("unroll") for (int _i = 0; _i < 2; ++_i) \
;         __builtin_amdgcn_global_load_lds((const unsigned*)((const char*)(gbase) + (voff)[_i]), (LAS unsigned*)(lds + (bufoff) + ldsw + _i * 8192), 16, 0, 0); } while (0)
; #define PG8_LDA(dst, b, h) do { _Pragma("unroll") for (int m = 0; m < 4; ++m) _Pragma("unroll") for (int k = 0; k < 2; ++k) dst[m][k] = *(const LAS bf16x8*)(lds + PG8_SA(b, h) + aoff + m * 2048 + k * 1024); } while (0)
; #define PG8_LDB(dst, b, h) do { _Pragma("unroll") for (int n = 0; n < 2; ++n) _Pragma("unroll") for (int k = 0; k < 2; ++k) dst[n][k] = *(const LAS bf16x8*)(lds + PG8_SB(b, h) + boff + n * 2048 + k * 1024); } while (0)
; #define PG8_MMA(ai, bj, At, Bt) do { __builtin_amdgcn_s_setprio(1); _Pragma("unroll") for (int m = 0; m < 4; ++m) _Pragma("unroll") for (int n = 0; n < 2; ++n) _Pragma("unroll") for (int k = 0; k < 2; ++k) \
;         acc[ai][bj][m][n] = __builtin_amdgcn_mfma_f32_16x16x32_bf16(Bt[n][k], At[m][k], acc[ai][bj][m][n], 0, 0, 0); __builtin_amdgcn_s_setprio(0); } while (0)
; #define PG8_WAIT_V(n) asm volatile("s_waitcnt vmcnt(" #n ")" ::: "memory")
; #define PG8_WAIT_L(n) asm volatile("s_waitcnt lgkmcnt(" #n ")" ::: "memory")
; #define PG8_BAR __builtin_amdgcn_s_barrier()
; #define PG8_SCHED __builtin_amdgcn_sched_barrier(0)
; template <class Epi, class Sched>
; __device__ __forceinline__ void gemm_phase(LAS unsigned char* lds, const Gemm g, const Sched& S, const Epi& E) {
;     ...
;             PG8_WAIT_V(6); PG8_BAR; PG8_MMA(1, 1, At, B1); PG8_BAR;
;             PG8_LDB(B0, 1, 0); PG8_SCHED; PG8_LDA(At, 1, 0); PG8_STAGE(PG8_SA(0, 1), a2 + hstep, voffA);
;             PG8_WAIT_L(8); PG8_BAR; PG8_WAIT_L(0); PG8_MMA(0, 0, At, B0); PG8_BAR; PG8_SCHED;
;             PG8_LDB(B1, 1, 1); PG8_STAGE(PG8_SB(1, 0), b3, voffB);
.Lpw_p10_go:
	s_barrier
	s_setprio 1
	v_mfma_f32_16x16x32_bf16 v[54:57], v[200:203], v[168:171], 0
	v_mfma_f32_16x16x32_bf16 v[50:53], v[212:215], v[168:171], 0
	v_mfma_f32_16x16x32_bf16 v[38:41], v[200:203], v[176:179], 0
	v_mfma_f32_16x16x32_bf16 v[34:37], v[212:215], v[176:179], 0
	v_mfma_f32_16x16x32_bf16 v[22:25], v[200:203], v[184:187], 0
	v_mfma_f32_16x16x32_bf16 v[18:21], v[212:215], v[184:187], 0
	v_mfma_f32_16x16x32_bf16 v[6:9], v[200:203], v[192:195], 0
	v_mfma_f32_16x16x32_bf16 v[2:5], v[212:215], v[192:195], 0
	v_mfma_f32_16x16x32_bf16 v[54:57], v[208:211], v[172:175], v[54:57]
	v_mfma_f32_16x16x32_bf16 v[50:53], v[216:219], v[172:175], v[50:53]
	v_mfma_f32_16x16x32_bf16 v[38:41], v[208:211], v[180:183], v[38:41]
	v_mfma_f32_16x16x32_bf16 v[34:37], v[216:219], v[180:183], v[34:37]
	v_mfma_f32_16x16x32_bf16 v[22:25], v[208:211], v[188:191], v[22:25]
	v_mfma_f32_16x16x32_bf16 v[18:21], v[216:219], v[188:191], v[18:21]
	v_mfma_f32_16x16x32_bf16 v[6:9], v[208:211], v[196:199], v[6:9]
	v_mfma_f32_16x16x32_bf16 v[2:5], v[216:219], v[196:199], v[2:5]
	s_setprio 0
	s_add_i32 s50, 0, 0x18000
	v_add_u32_e32 v164, s50, v146
	s_barrier
	ds_read_b128 v[152:155], v164
	ds_read_b128 v[156:159], v164 offset:1024
	ds_read_b128 v[160:163], v164 offset:2048
	ds_read_b128 v[164:167], v164 offset:3072
	s_add_u32 s22, s22, 0x80000
	s_addc_u32 s23, s23, 0
	s_mov_b32 m0, s35
	v_lshl_add_u64 v[200:201], s[22:23], 0, v[130:131]
	ds_read_b128 v[168:171], v150 offset:32768
	ds_read_b128 v[172:175], v150 offset:33792
	ds_read_b128 v[176:179], v150 offset:34816
	ds_read_b128 v[180:183], v150 offset:35840
	ds_read_b128 v[184:187], v150 offset:36864
	ds_read_b128 v[188:191], v150 offset:37888
	ds_read_b128 v[192:195], v150 offset:38912
	ds_read_b128 v[196:199], v150 offset:39936
	global_load_lds_dwordx4 v[200:201], off
	v_lshl_add_u64 v[200:201], s[22:23], 0, v[134:135]
	s_mov_b32 m0, s36
	s_nop 0
	global_load_lds_dwordx4 v[200:201], off
	s_waitcnt lgkmcnt(8)
	s_barrier
	s_waitcnt lgkmcnt(0)
	s_setprio 1
	s_waitcnt lgkmcnt(0)
	v_mfma_f32_16x16x32_bf16 v[126:129], v[152:155], v[168:171], v[126:129]
	v_mfma_f32_16x16x32_bf16 v[122:125], v[160:163], v[168:171], v[122:125]
	v_mfma_f32_16x16x32_bf16 v[110:113], v[152:155], v[176:179], v[110:113]
	v_mfma_f32_16x16x32_bf16 v[106:109], v[160:163], v[176:179], v[106:109]
	v_mfma_f32_16x16x32_bf16 v[94:97], v[152:155], v[184:187], v[94:97]
	v_mfma_f32_16x16x32_bf16 v[90:93], v[160:163], v[184:187], v[90:93]
	v_mfma_f32_16x16x32_bf16 v[78:81], v[152:155], v[192:195], v[78:81]
	v_mfma_f32_16x16x32_bf16 v[74:77], v[160:163], v[192:195], v[74:77]
	v_mfma_f32_16x16x32_bf16 v[126:129], v[156:159], v[172:175], v[126:129]
	v_mfma_f32_16x16x32_bf16 v[122:125], v[164:167], v[172:175], v[122:125]
	v_mfma_f32_16x16x32_bf16 v[110:113], v[156:159], v[180:183], v[110:113]
	v_mfma_f32_16x16x32_bf16 v[106:109], v[164:167], v[180:183], v[106:109]
	v_mfma_f32_16x16x32_bf16 v[94:97], v[156:159], v[188:191], v[94:97]
	v_mfma_f32_16x16x32_bf16 v[90:93], v[164:167], v[188:191], v[90:93]
	v_mfma_f32_16x16x32_bf16 v[78:81], v[156:159], v[196:199], v[78:81]
	v_mfma_f32_16x16x32_bf16 v[74:77], v[164:167], v[196:199], v[74:77]
	s_setprio 0
	s_barrier
	s_add_i32 s22, 0, 0x1c000
	s_add_i32 s23, s50, s27
	v_add_u32_e32 v207, s22, v146
	v_lshl_add_u64 v[204:205], v[204:205], 0, s[6:7]
	s_mov_b32 m0, s23
	ds_read_b128 v[200:203], v207
	ds_read_b128 v[208:211], v207 offset:1024
	ds_read_b128 v[212:215], v207 offset:2048
	ds_read_b128 v[216:219], v207 offset:3072
	global_load_lds_dwordx4 v[204:205], off
	v_lshl_add_u64 v[204:205], v[220:221], 0, s[6:7]
	s_add_i32 m0, s23, 0x2000
	s_nop 0
	global_load_lds_dwordx4 v[204:205], off
	s_barrier
; #define PG8_STAGE(bufoff, gbase, voff) do { _Pragma("unroll") for (int _i = 0; _i < 2; ++_i) \
;         __builtin_amdgcn_global_load_lds((const unsigned*)((const char*)(gbase) + (voff)[_i]), (LAS unsigned*)(lds + (bufoff) + ldsw + _i * 8192), 16, 0, 0); } while (0)
; #define PG8_LDA(dst, b, h) do { _Pragma("unroll") for (int m = 0; m < 4; ++m) _Pragma("unroll") for (int k = 0; k < 2; ++k) dst[m][k] = *(const LAS bf16x8*)(lds + PG8_SA(b, h) + aoff + m * 2048 + k * 1024); } while (0)
; #define PG8_MMA(ai, bj, At, Bt) do { __builtin_amdgcn_s_setprio(1); _Pragma("unroll") for (int m = 0; m < 4; ++m) _Pragma("unroll") for (int n = 0; n < 2; ++n) _Pragma("unroll") for (int k = 0; k < 2; ++k) \
;         acc[ai][bj][m][n] = __builtin_amdgcn_mfma_f32_16x16x32_bf16(Bt[n][k], At[m][k], acc[ai][bj][m][n], 0, 0, 0); __builtin_amdgcn_s_setprio(0); } while (0)
; #define PG8_WAIT_V(n) asm volatile("s_waitcnt vmcnt(" #n ")" ::: "memory")
; #define PG8_WAIT_L(n) asm volatile("s_waitcnt lgkmcnt(" #n ")" ::: "memory")
; #define PG8_BAR __builtin_amdgcn_s_barrier()
; #define PG8_SCHED __builtin_amdgcn_sched_barrier(0)
; template <class Epi, class Sched>
; __device__ __forceinline__ void gemm_phase(LAS unsigned char* lds, const Gemm g, const Sched& S, const Epi& E) {
;     ...
;             PG8_BAR; PG8_WAIT_L(0); PG8_MMA(0, 1, At, B1); PG8_BAR;
;             PG8_LDA(At, 1, 1); PG8_STAGE(PG8_SA(1, 0), a3, voffA);
;             PG8_BAR; PG8_WAIT_L(0); PG8_MMA(1, 0, At, B0); PG8_BAR; PG8_SCHED;
;             PG8_STAGE(PG8_SB(1, 1), b3 + hstep, voffB);
;             PG8_WAIT_V(6); PG8_BAR; PG8_MMA(1, 1, At, B1); PG8_BAR;
	s_waitcnt lgkmcnt(0)
	s_setprio 1
	s_waitcnt lgkmcnt(0)
	v_mfma_f32_16x16x32_bf16 v[118:121], v[200:203], v[168:171], v[118:121]
	v_mfma_f32_16x16x32_bf16 v[114:117], v[212:215], v[168:171], v[114:117]
	v_mfma_f32_16x16x32_bf16 v[102:105], v[200:203], v[176:179], v[102:105]
	v_mfma_f32_16x16x32_bf16 v[98:101], v[212:215], v[176:179], v[98:101]
	v_mfma_f32_16x16x32_bf16 v[86:89], v[200:203], v[184:187], v[86:89]
	v_mfma_f32_16x16x32_bf16 v[82:85], v[212:215], v[184:187], v[82:85]
	v_mfma_f32_16x16x32_bf16 v[70:73], v[200:203], v[192:195], v[70:73]
	v_mfma_f32_16x16x32_bf16 v[66:69], v[212:215], v[192:195], v[66:69]
	v_mfma_f32_16x16x32_bf16 v[118:121], v[208:211], v[172:175], v[118:121]
	v_mfma_f32_16x16x32_bf16 v[114:117], v[216:219], v[172:175], v[114:117]
	v_mfma_f32_16x16x32_bf16 v[102:105], v[208:211], v[180:183], v[102:105]
	v_mfma_f32_16x16x32_bf16 v[98:101], v[216:219], v[180:183], v[98:101]
	v_mfma_f32_16x16x32_bf16 v[86:89], v[208:211], v[188:191], v[86:89]
	v_mfma_f32_16x16x32_bf16 v[82:85], v[216:219], v[188:191], v[82:85]
	v_mfma_f32_16x16x32_bf16 v[70:73], v[208:211], v[196:199], v[70:73]
	v_mfma_f32_16x16x32_bf16 v[66:69], v[216:219], v[196:199], v[66:69]
	s_setprio 0
	s_mov_b32 m0, s37
	v_lshl_add_u64 v[204:205], v[222:223], 0, s[6:7]
	s_waitcnt vmcnt(10)
	s_barrier
	ds_read_b128 v[168:171], v150 offset:49152
	ds_read_b128 v[172:175], v150 offset:50176
	ds_read_b128 v[176:179], v150 offset:51200
	ds_read_b128 v[180:183], v150 offset:52224
	ds_read_b128 v[184:187], v150 offset:53248
	ds_read_b128 v[188:191], v150 offset:54272
	ds_read_b128 v[192:195], v150 offset:55296
	ds_read_b128 v[196:199], v150 offset:56320
	global_load_lds_dwordx4 v[204:205], off
	v_lshl_add_u64 v[204:205], v[224:225], 0, s[6:7]
	s_mov_b32 m0, s38
	s_nop 0
	global_load_lds_dwordx4 v[204:205], off
	s_barrier
	s_waitcnt lgkmcnt(0)
	s_setprio 1
	s_waitcnt lgkmcnt(0)
	v_mfma_f32_16x16x32_bf16 v[62:65], v[152:155], v[168:171], v[62:65]
	v_mfma_f32_16x16x32_bf16 v[58:61], v[160:163], v[168:171], v[58:61]
	v_mfma_f32_16x16x32_bf16 v[46:49], v[152:155], v[176:179], v[46:49]
	v_mfma_f32_16x16x32_bf16 v[42:45], v[160:163], v[176:179], v[42:45]
	v_mfma_f32_16x16x32_bf16 v[30:33], v[152:155], v[184:187], v[30:33]
	v_mfma_f32_16x16x32_bf16 v[26:29], v[160:163], v[184:187], v[26:29]
	v_mfma_f32_16x16x32_bf16 v[14:17], v[152:155], v[192:195], v[14:17]
	v_mfma_f32_16x16x32_bf16 v[10:13], v[160:163], v[192:195], v[10:13]
	v_mfma_f32_16x16x32_bf16 v[62:65], v[156:159], v[172:175], v[62:65]
	v_mfma_f32_16x16x32_bf16 v[58:61], v[164:167], v[172:175], v[58:61]
	v_mfma_f32_16x16x32_bf16 v[46:49], v[156:159], v[180:183], v[46:49]
	v_mfma_f32_16x16x32_bf16 v[42:45], v[164:167], v[180:183], v[42:45]
	v_mfma_f32_16x16x32_bf16 v[30:33], v[156:159], v[188:191], v[30:33]
	v_mfma_f32_16x16x32_bf16 v[26:29], v[164:167], v[188:191], v[26:29]
	v_mfma_f32_16x16x32_bf16 v[14:17], v[156:159], v[196:199], v[14:17]
	v_mfma_f32_16x16x32_bf16 v[10:13], v[164:167], v[196:199], v[10:13]
	s_setprio 0
	s_barrier
	s_add_u32 s20, s20, 0x80080
	s_addc_u32 s21, s21, 0
	s_add_i32 s22, s22, s27
	v_lshl_add_u64 v[152:153], s[20:21], 0, v[132:133]
	s_mov_b32 m0, s22
	s_nop 0
	global_load_lds_dwordx4 v[152:153], off
	v_lshl_add_u64 v[152:153], s[20:21], 0, v[136:137]
	s_add_i32 m0, s22, 0x2000
	s_nop 0
	global_load_lds_dwordx4 v[152:153], off
	s_waitcnt vmcnt(6)
	s_barrier
	s_setprio 1
	v_mfma_f32_16x16x32_bf16 v[54:57], v[200:203], v[168:171], v[54:57]
	v_mfma_f32_16x16x32_bf16 v[50:53], v[212:215], v[168:171], v[50:53]
	v_mfma_f32_16x16x32_bf16 v[38:41], v[200:203], v[176:179], v[38:41]
	v_mfma_f32_16x16x32_bf16 v[34:37], v[212:215], v[176:179], v[34:37]
	v_mfma_f32_16x16x32_bf16 v[22:25], v[200:203], v[184:187], v[22:25]
	v_mfma_f32_16x16x32_bf16 v[18:21], v[212:215], v[184:187], v[18:21]
	v_mfma_f32_16x16x32_bf16 v[6:9], v[200:203], v[192:195], v[6:9]
	v_mfma_f32_16x16x32_bf16 v[2:5], v[212:215], v[192:195], v[2:5]
	v_mfma_f32_16x16x32_bf16 v[54:57], v[208:211], v[172:175], v[54:57]
	v_mfma_f32_16x16x32_bf16 v[50:53], v[216:219], v[172:175], v[50:53]
	v_mfma_f32_16x16x32_bf16 v[38:41], v[208:211], v[180:183], v[38:41]
	v_mfma_f32_16x16x32_bf16 v[34:37], v[216:219], v[180:183], v[34:37]
	v_mfma_f32_16x16x32_bf16 v[22:25], v[208:211], v[188:191], v[22:25]
	v_mfma_f32_16x16x32_bf16 v[18:21], v[216:219], v[188:191], v[18:21]
	v_mfma_f32_16x16x32_bf16 v[6:9], v[208:211], v[196:199], v[6:9]
	v_mfma_f32_16x16x32_bf16 v[2:5], v[216:219], v[196:199], v[2:5]
	s_setprio 0
	s_add_i32 s49, s49, 2
	s_add_u32 s18, s18, 0x100
	s_addc_u32 s19, s19, 0
	s_add_u32 s47, s47, 0x100
	s_addc_u32 s48, s48, 0
	s_cmp_gt_u32 s49, 29
	s_barrier
